# prep_weights LDS transpose tile: 16-byte column chunks XOR-swizzled by ((row>>3)&3) to spread the transposed ds_write_b16 over the banks (both instances)
# speedup vs baseline: 1.0125x; 1.0028x over previous
; #define LAS __attribute__((address_space(3)))
; __device__ __forceinline__ bf16_t f2bf(float f) { return (bf16_t)(pk2(f, f) & 0xFFFFu); }
; __device__ NOINL void prep_weights(const LAS Params* lp, int l, LAS unsigned char* lds) {
;     ...
;                 const int kk = pass * 32 + (tid >> 4), nn = q * 64 + (tid & 15) * 4;
;                 v[pass][q] = (n0 + nn < N) ? *(const f32x4*)(W + (size_t)(k0 + kk) * N + n0 + nn) : (f32x4){0.f, 0.f, 0.f, 0.f};
;             }
;     };
;     int it = blockIdx.x, buf = 0;
;     __syncthreads();
;     if (it < NI) { resolve(it); issue(); }
;     for (; it < NI; it += gridDim.x) {
;         LAS bf16_t* ts = (LAS bf16_t*)(lds + buf * 36864);
; #pragma unroll
;         for (int pass = 0; pass < 2; ++pass)
; #pragma unroll
;             for (int q = 0; q < 4; ++q) {
;                 const int kk = pass * 32 + (tid >> 4), nn = q * 64 + (tid & 15) * 4;
;                 ts[(nn + 0) * 72 + kk] = f2bf(v[pass][q][0]); ts[(nn + 1) * 72 + kk] = f2bf(v[pass][q][1]); ts[(nn + 2) * 72 + kk] = f2bf(v[pass][q][2]); ts[(nn + 3) * 72 + kk] = f2bf(v[pass][q][3]);
;             }
;         const int nn = tid >> 1, k32 = (tid & 1) * 32;
;         const bool ok = n0 + nn < N;
;         bf16_t* d = Wt + (size_t)wt_map(mode, ok ? n0 + nn : 0) * K + k0 + k32;
.LBB0_43:
	v_cndmask_b32_e64 v1, 0, 1, s[12:13]
	v_cmp_ne_u32_e64 s[6:7], 1, v1
	s_andn2_b64 vcc, exec, s[12:13]
	s_nop 0
	v_writelane_b32 v252, s6, 9
	s_nop 1
	v_writelane_b32 v252, s7, 10
	s_cbranch_vccnz .LBB0_90
	v_lshlrev_b32_e32 v10, 2, v38
	v_and_b32_e32 v40, 60, v10
	s_movk_i32 s6, 0x90
	v_mov_b32_e32 v11, 0x2400
	v_lshlrev_b32_e32 v10, 5, v38
	v_mad_u32_u24 v51, v40, s6, v11
	v_mov_b32_e32 v11, 0x4800
	v_ashrrev_i32_e32 v1, 4, v38
	v_ashrrev_i32_e32 v39, 1, v38
	v_and_b32_e32 v12, 32, v10
	v_mad_u32_u24 v52, v40, s6, v11
	v_mov_b32_e32 v11, 0x6c00
	v_mov_b32_e32 v10, 0
	v_or_b32_e32 v41, 64, v40
	v_or_b32_e32 v46, 0x80, v40
	v_or_b32_e32 v47, 0xc0, v40
	v_add_u32_e32 v48, 32, v1
	v_mul_lo_u32 v49, v39, s6
	v_mul_u32_u24_e32 v50, 0x90, v40
	v_mad_u32_u24 v53, v40, s6, v11
	s_mov_b32 s44, 0
	v_bfe_u32 v54, v38, 1, 2
	v_lshlrev_b32_e32 v54, 3, v54
	v_xor_b32_e32 v54, v54, v1
	v_lshlrev_b32_e32 v54, 1, v54
	s_movk_i32 s45, 0xb00
	s_movk_i32 s46, 0xaff
	s_movk_i32 s47, 0xb0f
	v_lshlrev_b32_e32 v42, 1, v12
	v_mov_b32_e32 v55, 0x80
	s_mov_b32 s48, s2
	s_branch .LBB0_46

; #define LAS __attribute__((address_space(3)))
; __device__ NOINL void prep_weights(const LAS Params* lp, int l, LAS unsigned char* lds) {
;     ...
;         __syncthreads();
;         if (ok) {
; #pragma unroll
;             for (int q = 0; q < 4; ++q) *(u32x4*)(d + q * 8) = *(const LAS u32x4*)(ts + nn * 72 + k32 + q * 8);
;         }
.LBB0_87:
	s_waitcnt lgkmcnt(0)
	s_barrier
	s_and_saveexec_b64 s[10:11], s[8:9]
	s_cbranch_execz .LBB0_45
	v_add3_u32 v11, s50, v49, v42
	v_bfe_u32 v120, v38, 4, 2
	v_lshlrev_b32_e32 v120, 4, v120
	v_xor_b32_e32 v121, 16, v120
	v_xor_b32_e32 v122, 32, v120
	v_xor_b32_e32 v123, 48, v120
	v_add_u32_e32 v120, v11, v120
	v_add_u32_e32 v121, v11, v121
	v_add_u32_e32 v122, v11, v122
	v_add_u32_e32 v123, v11, v123
	ds_read_b128 v[56:59], v120
	ds_read_b128 v[60:63], v121
	ds_read_b128 v[64:67], v122
	ds_read_b128 v[68:71], v123
	v_mad_i64_i32 v[12:13], s[8:9], v43, s7, 0
	v_lshl_add_u64 v[12:13], v[12:13], 1, s[36:37]
	s_ashr_i32 s7, s6, 31
	v_lshl_add_u64 v[12:13], s[6:7], 1, v[12:13]
	v_mov_b32_e32 v43, v10
	v_lshl_add_u64 v[12:13], v[12:13], 0, v[42:43]
	s_waitcnt lgkmcnt(3)
	global_store_dwordx4 v[12:13], v[56:59], off
	s_waitcnt lgkmcnt(2)
	global_store_dwordx4 v[12:13], v[60:63], off offset:16
	s_waitcnt lgkmcnt(1)
	global_store_dwordx4 v[12:13], v[64:67], off offset:32
	s_waitcnt lgkmcnt(0)
	global_store_dwordx4 v[12:13], v[68:71], off offset:48
	s_branch .LBB0_45

; __device__ __forceinline__ bf16_t f2bf(float f) { return (bf16_t)(pk2(f, f) & 0xFFFFu); }
; __device__ __forceinline__ int wt_map(int mode, int n) {
;     if (mode == 1) return n < 2816 ? n : (n < 2832 ? 3840 + (n - 2816) : n - 16);
;     if (mode == 2) { const int j = n < FFH ? n : n - FFH; return (j >> 7) * 256 + (n < FFH ? 0 : 128) + (j & 127); }
; __device__ NOINL void prep_weights(const LAS Params* lp, int l, LAS unsigned char* lds) {
;     ...
; #pragma unroll
;         for (int pass = 0; pass < 2; ++pass)
; #pragma unroll
;             for (int q = 0; q < 4; ++q) {
;                 const int kk = pass * 32 + (tid >> 4), nn = q * 64 + (tid & 15) * 4;
;                 ts[(nn + 0) * 72 + kk] = f2bf(v[pass][q][0]); ts[(nn + 1) * 72 + kk] = f2bf(v[pass][q][1]); ts[(nn + 2) * 72 + kk] = f2bf(v[pass][q][2]); ts[(nn + 3) * 72 + kk] = f2bf(v[pass][q][3]);
;             }
;         const int nn = tid >> 1, k32 = (tid & 1) * 32;
;         const bool ok = n0 + nn < N;
;         bf16_t* d = Wt + (size_t)wt_map(mode, ok ? n0 + nn : 0) * K + k0 + k32;
.LBB0_351:
	s_mov_b32 s18, s3
	s_mul_i32 s3, s4, 0x9000
	s_add_i32 s19, s3, 0
	v_bfe_u32 v2, v40, 1, 2
	v_lshlrev_b32_e32 v2, 3, v2
	v_xor_b32_e32 v2, v2, v41
	v_lshlrev_b32_e32 v2, 1, v2
	s_waitcnt vmcnt(0)
	v_cvt_pk_bf16_f32 v0, v8, s0
	v_add3_u32 v3, s19, v53, v2
	ds_write_b16 v3, v0
	v_cvt_pk_bf16_f32 v0, v9, s0
	ds_write_b16 v3, v0 offset:144
	v_cvt_pk_bf16_f32 v0, v10, s0
	ds_write_b16 v3, v0 offset:288
	v_cvt_pk_bf16_f32 v0, v11, s0
	ds_write_b16 v3, v0 offset:432
	v_cvt_pk_bf16_f32 v0, v12, s0
	v_add3_u32 v45, s19, v54, v2
	ds_write_b16 v45, v0
	v_cvt_pk_bf16_f32 v0, v13, s0
	ds_write_b16 v45, v0 offset:144
	v_cvt_pk_bf16_f32 v0, v14, s0
	ds_write_b16 v45, v0 offset:288
	v_cvt_pk_bf16_f32 v0, v15, s0
	ds_write_b16 v45, v0 offset:432
	v_cvt_pk_bf16_f32 v0, v16, s0
	v_add3_u32 v46, s19, v55, v2
	ds_write_b16 v46, v0
	v_cvt_pk_bf16_f32 v0, v17, s0
	ds_write_b16 v46, v0 offset:144
	v_cvt_pk_bf16_f32 v0, v18, s0
	ds_write_b16 v46, v0 offset:288
	v_cvt_pk_bf16_f32 v0, v19, s0
	ds_write_b16 v46, v0 offset:432
	v_cvt_pk_bf16_f32 v0, v20, s0
	v_add3_u32 v2, s19, v56, v2
	ds_write_b16 v2, v0
	v_cvt_pk_bf16_f32 v0, v21, s0
	ds_write_b16 v2, v0 offset:144
	v_cvt_pk_bf16_f32 v0, v22, s0
	ds_write_b16 v2, v0 offset:288
	v_cvt_pk_bf16_f32 v0, v23, s0
	ds_write_b16 v2, v0 offset:432
	v_cvt_pk_bf16_f32 v0, v24, s0
	ds_write_b16 v3, v0 offset:64
	v_cvt_pk_bf16_f32 v0, v25, s0
	ds_write_b16 v3, v0 offset:208
	v_cvt_pk_bf16_f32 v0, v26, s0
	ds_write_b16 v3, v0 offset:352
	v_cvt_pk_bf16_f32 v0, v27, s0
	ds_write_b16 v3, v0 offset:496
	v_cvt_pk_bf16_f32 v0, v28, s0
	ds_write_b16 v45, v0 offset:64
	v_cvt_pk_bf16_f32 v0, v29, s0
	ds_write_b16 v45, v0 offset:208
	v_cvt_pk_bf16_f32 v0, v30, s0
	ds_write_b16 v45, v0 offset:352
	v_cvt_pk_bf16_f32 v0, v31, s0
	ds_write_b16 v45, v0 offset:496
	v_cvt_pk_bf16_f32 v0, v32, s0
	ds_write_b16 v46, v0 offset:64
	v_cvt_pk_bf16_f32 v0, v33, s0
	ds_write_b16 v46, v0 offset:208
	v_cvt_pk_bf16_f32 v0, v34, s0
	ds_write_b16 v46, v0 offset:352
	v_cvt_pk_bf16_f32 v0, v35, s0
	ds_write_b16 v46, v0 offset:496
	v_cvt_pk_bf16_f32 v0, v36, s0
	ds_write_b16 v2, v0 offset:64
	v_cvt_pk_bf16_f32 v0, v37, s0
	ds_write_b16 v2, v0 offset:208
	v_cvt_pk_bf16_f32 v0, v38, s0
	ds_write_b16 v2, v0 offset:352
	v_cvt_pk_bf16_f32 v0, v39, s0
	ds_write_b16 v2, v0 offset:496
	v_add_u32_e32 v0, s60, v43
	v_cmp_gt_i32_e64 s[44:45], s1, v0
	s_mov_b32 s70, s6
	s_mov_b64 s[72:73], s[58:59]
	v_cndmask_b32_e64 v0, 0, v0, s[44:45]
	s_cmp_lt_i32 s0, 2
	s_mov_b64 s[46:47], -1
	s_cbranch_scc1 .LBB0_355
	s_cmp_eq_u32 s0, 2
	v_mov_b32_e32 v45, v0
	s_cbranch_scc0 .LBB0_354
	s_movk_i32 s3, 0xb00
	v_add_u32_e32 v2, 0xfffff500, v0
	v_cmp_gt_i32_e32 vcc, s3, v0
	s_nop 1
	v_cndmask_b32_e32 v2, v2, v0, vcc
	v_lshlrev_b32_e32 v3, 1, v2
	v_and_b32_e32 v3, 0xffffff00, v3
	v_cndmask_b32_e64 v45, v226, 0, vcc
	v_and_b32_e32 v2, 0x7f, v2
	v_or3_b32 v45, v2, v45, v3

; #define LAS __attribute__((address_space(3)))
; __device__ NOINL void prep_weights(const LAS Params* lp, int l, LAS unsigned char* lds) {
;     ...
;         __syncthreads();
;         if (ok) {
; #pragma unroll
;             for (int q = 0; q < 4; ++q) *(u32x4*)(d + q * 8) = *(const LAS u32x4*)(ts + nn * 72 + k32 + q * 8);
;         }
.LBB0_392:
	s_waitcnt lgkmcnt(0)
	s_barrier
	s_and_saveexec_b64 s[46:47], s[44:45]
	s_cbranch_execz .LBB0_350
	v_add3_u32 v0, s19, v52, v44
	v_bfe_u32 v94, v40, 4, 2
	v_lshlrev_b32_e32 v94, 4, v94
	v_xor_b32_e32 v95, 16, v94
	v_xor_b32_e32 v96, 32, v94
	v_xor_b32_e32 v97, 48, v94
	v_add_u32_e32 v94, v0, v94
	v_add_u32_e32 v95, v0, v95
	v_add_u32_e32 v96, v0, v96
	v_add_u32_e32 v97, v0, v97
	ds_read_b128 v[58:61], v94
	ds_read_b128 v[62:65], v95
	ds_read_b128 v[66:69], v96
	ds_read_b128 v[70:73], v97
	v_mad_i64_i32 v[2:3], s[20:21], v45, s18, 0
	v_lshl_add_u64 v[2:3], v[2:3], 1, s[72:73]
	s_ashr_i32 s71, s70, 31
	v_lshl_add_u64 v[2:3], s[70:71], 1, v[2:3]
	v_mov_b32_e32 v45, v1
	v_lshl_add_u64 v[2:3], v[2:3], 0, v[44:45]
	s_waitcnt lgkmcnt(3)
	global_store_dwordx4 v[2:3], v[58:61], off
	s_waitcnt lgkmcnt(2)
	global_store_dwordx4 v[2:3], v[62:65], off offset:16
	s_waitcnt lgkmcnt(1)
	global_store_dwordx4 v[2:3], v[66:69], off offset:32
	s_waitcnt lgkmcnt(0)
	global_store_dwordx4 v[2:3], v[70:73], off offset:48
	s_branch .LBB0_350
